# nt (non-temporal) hint on the proj and gate-up epilogue stores
# speedup vs baseline: 1.0016x; 1.0016x over previous
.Lpj_scales_ready:
	s_movk_i32 s33, 0x3800
	v_mov_b64_e32 v[170:171], s[20:21]
	v_lshl_or_b32 v176, s30, 8, v163
	v_ashrrev_i32_e32 v177, 31, v176
	v_lshlrev_b64 v[176:177], 1, v[176:177]
	v_mad_i64_i32 v[204:205], s[28:29], v168, s33, v[170:171]
	v_mad_i64_i32 v[206:207], s[28:29], v164, s33, v[170:171]
	v_mad_i64_i32 v[208:209], s[28:29], v160, s33, v[170:171]
	v_mad_i64_i32 v[210:211], s[28:29], v156, s33, v[170:171]
	v_mad_i64_i32 v[212:213], s[28:29], v154, s33, v[170:171]
	v_mad_i64_i32 v[214:215], s[28:29], v150, s33, v[170:171]
	v_mad_i64_i32 v[216:217], s[28:29], v146, s33, v[170:171]
	v_mad_i64_i32 v[218:219], s[28:29], v142, s33, v[170:171]
	v_lshl_add_u64 v[204:205], v[204:205], 0, v[176:177]
	v_lshl_add_u64 v[206:207], v[206:207], 0, v[176:177]
	v_lshl_add_u64 v[208:209], v[208:209], 0, v[176:177]
	v_lshl_add_u64 v[210:211], v[210:211], 0, v[176:177]
	v_lshl_add_u64 v[212:213], v[212:213], 0, v[176:177]
	v_lshl_add_u64 v[214:215], v[214:215], 0, v[176:177]
	v_lshl_add_u64 v[216:217], v[216:217], 0, v[176:177]
	v_lshl_add_u64 v[218:219], v[218:219], 0, v[176:177]
	s_mov_b64 s[42:43], -1
	s_andn2_b64 vcc, exec, s[36:37]
	v_pk_mul_f32 v[128:129], v[128:129], v[228:229] op_sel_hi:[1,0]
	v_pk_mul_f32 v[130:131], v[130:131], v[228:229] op_sel_hi:[1,0]
	v_pk_mul_f32 v[124:125], v[124:125], v[228:229] op_sel_hi:[1,0]
	v_pk_mul_f32 v[126:127], v[126:127], v[228:229] op_sel_hi:[1,0]
	v_cvt_pk_bf16_f32 v128, v128, v129
	v_cvt_pk_bf16_f32 v129, v130, v131
	v_cvt_pk_bf16_f32 v130, v124, v125
	v_cvt_pk_bf16_f32 v131, v126, v127
	s_waitcnt vmcnt(0)
	global_store_dwordx4 v[204:205], v[128:131], off nt
	v_pk_mul_f32 v[120:121], v[120:121], v[228:229] op_sel_hi:[1,0]
	v_pk_mul_f32 v[122:123], v[122:123], v[228:229] op_sel_hi:[1,0]
	v_pk_mul_f32 v[112:113], v[112:113], v[228:229] op_sel_hi:[1,0]
	v_pk_mul_f32 v[114:115], v[114:115], v[228:229] op_sel_hi:[1,0]
	v_cvt_pk_bf16_f32 v120, v120, v121
	v_cvt_pk_bf16_f32 v121, v122, v123
	v_cvt_pk_bf16_f32 v122, v112, v113
	v_cvt_pk_bf16_f32 v123, v114, v115
	global_store_dwordx4 v[204:205], v[120:123], off offset:256 nt
	v_pk_mul_f32 v[116:117], v[116:117], v[230:231] op_sel_hi:[1,0]
	v_pk_mul_f32 v[118:119], v[118:119], v[230:231] op_sel_hi:[1,0]
	v_pk_mul_f32 v[108:109], v[108:109], v[230:231] op_sel_hi:[1,0]
	v_pk_mul_f32 v[110:111], v[110:111], v[230:231] op_sel_hi:[1,0]
	v_cvt_pk_bf16_f32 v116, v116, v117
	v_cvt_pk_bf16_f32 v117, v118, v119
	v_cvt_pk_bf16_f32 v118, v108, v109
	v_cvt_pk_bf16_f32 v119, v110, v111
	global_store_dwordx4 v[206:207], v[116:119], off nt
	v_pk_mul_f32 v[104:105], v[104:105], v[230:231] op_sel_hi:[1,0]
	v_pk_mul_f32 v[106:107], v[106:107], v[230:231] op_sel_hi:[1,0]
	v_pk_mul_f32 v[96:97], v[96:97], v[230:231] op_sel_hi:[1,0]
	v_pk_mul_f32 v[98:99], v[98:99], v[230:231] op_sel_hi:[1,0]
	v_cvt_pk_bf16_f32 v104, v104, v105
	v_cvt_pk_bf16_f32 v105, v106, v107
	v_cvt_pk_bf16_f32 v106, v96, v97
	v_cvt_pk_bf16_f32 v107, v98, v99
	global_store_dwordx4 v[206:207], v[104:107], off offset:256 nt
	v_pk_mul_f32 v[100:101], v[100:101], v[238:239] op_sel_hi:[1,0]
	v_pk_mul_f32 v[102:103], v[102:103], v[238:239] op_sel_hi:[1,0]
	v_pk_mul_f32 v[92:93], v[92:93], v[238:239] op_sel_hi:[1,0]
	v_pk_mul_f32 v[94:95], v[94:95], v[238:239] op_sel_hi:[1,0]
	v_cvt_pk_bf16_f32 v100, v100, v101
	v_cvt_pk_bf16_f32 v101, v102, v103
	v_cvt_pk_bf16_f32 v102, v92, v93
	v_cvt_pk_bf16_f32 v103, v94, v95
	global_store_dwordx4 v[208:209], v[100:103], off nt
	v_pk_mul_f32 v[88:89], v[88:89], v[238:239] op_sel_hi:[1,0]
	v_pk_mul_f32 v[90:91], v[90:91], v[238:239] op_sel_hi:[1,0]
	v_pk_mul_f32 v[80:81], v[80:81], v[238:239] op_sel_hi:[1,0]
	v_pk_mul_f32 v[82:83], v[82:83], v[238:239] op_sel_hi:[1,0]
	v_cvt_pk_bf16_f32 v88, v88, v89
	v_cvt_pk_bf16_f32 v89, v90, v91
	v_cvt_pk_bf16_f32 v90, v80, v81
	v_cvt_pk_bf16_f32 v91, v82, v83
	global_store_dwordx4 v[208:209], v[88:91], off offset:256 nt
	v_pk_mul_f32 v[84:85], v[84:85], v[242:243] op_sel_hi:[1,0]
	v_pk_mul_f32 v[86:87], v[86:87], v[242:243] op_sel_hi:[1,0]
	v_pk_mul_f32 v[76:77], v[76:77], v[242:243] op_sel_hi:[1,0]
	v_pk_mul_f32 v[78:79], v[78:79], v[242:243] op_sel_hi:[1,0]
	v_cvt_pk_bf16_f32 v84, v84, v85
	v_cvt_pk_bf16_f32 v85, v86, v87
	v_cvt_pk_bf16_f32 v86, v76, v77
	v_cvt_pk_bf16_f32 v87, v78, v79
	global_store_dwordx4 v[210:211], v[84:87], off nt
	v_pk_mul_f32 v[72:73], v[72:73], v[242:243] op_sel_hi:[1,0]
	v_pk_mul_f32 v[74:75], v[74:75], v[242:243] op_sel_hi:[1,0]
	v_pk_mul_f32 v[68:69], v[68:69], v[242:243] op_sel_hi:[1,0]
	v_pk_mul_f32 v[70:71], v[70:71], v[242:243] op_sel_hi:[1,0]
	v_cvt_pk_bf16_f32 v72, v72, v73
	v_cvt_pk_bf16_f32 v73, v74, v75
	v_cvt_pk_bf16_f32 v74, v68, v69
	v_cvt_pk_bf16_f32 v75, v70, v71
	global_store_dwordx4 v[210:211], v[72:75], off offset:256 nt
	v_pk_mul_f32 v[64:65], v[64:65], v[244:245] op_sel_hi:[1,0]
	v_pk_mul_f32 v[66:67], v[66:67], v[244:245] op_sel_hi:[1,0]
	v_pk_mul_f32 v[60:61], v[60:61], v[244:245] op_sel_hi:[1,0]
	v_pk_mul_f32 v[62:63], v[62:63], v[244:245] op_sel_hi:[1,0]
	v_cvt_pk_bf16_f32 v64, v64, v65
	v_cvt_pk_bf16_f32 v65, v66, v67
	v_cvt_pk_bf16_f32 v66, v60, v61
	v_cvt_pk_bf16_f32 v67, v62, v63
	global_store_dwordx4 v[212:213], v[64:67], off nt
	v_pk_mul_f32 v[56:57], v[56:57], v[244:245] op_sel_hi:[1,0]
	v_pk_mul_f32 v[58:59], v[58:59], v[244:245] op_sel_hi:[1,0]
	v_pk_mul_f32 v[48:49], v[48:49], v[244:245] op_sel_hi:[1,0]
	v_pk_mul_f32 v[50:51], v[50:51], v[244:245] op_sel_hi:[1,0]
	v_cvt_pk_bf16_f32 v56, v56, v57
	v_cvt_pk_bf16_f32 v57, v58, v59
	v_cvt_pk_bf16_f32 v58, v48, v49
	v_cvt_pk_bf16_f32 v59, v50, v51
	global_store_dwordx4 v[212:213], v[56:59], off offset:256 nt
	v_pk_mul_f32 v[52:53], v[52:53], v[246:247] op_sel_hi:[1,0]
	v_pk_mul_f32 v[54:55], v[54:55], v[246:247] op_sel_hi:[1,0]
	v_pk_mul_f32 v[44:45], v[44:45], v[246:247] op_sel_hi:[1,0]
	v_pk_mul_f32 v[46:47], v[46:47], v[246:247] op_sel_hi:[1,0]
	v_cvt_pk_bf16_f32 v52, v52, v53
	v_cvt_pk_bf16_f32 v53, v54, v55
	v_cvt_pk_bf16_f32 v54, v44, v45
	v_cvt_pk_bf16_f32 v55, v46, v47
	global_store_dwordx4 v[214:215], v[52:55], off nt
	v_pk_mul_f32 v[40:41], v[40:41], v[246:247] op_sel_hi:[1,0]
	v_pk_mul_f32 v[42:43], v[42:43], v[246:247] op_sel_hi:[1,0]
	v_pk_mul_f32 v[32:33], v[32:33], v[246:247] op_sel_hi:[1,0]
	v_pk_mul_f32 v[34:35], v[34:35], v[246:247] op_sel_hi:[1,0]
	v_cvt_pk_bf16_f32 v40, v40, v41
	v_cvt_pk_bf16_f32 v41, v42, v43
	v_cvt_pk_bf16_f32 v42, v32, v33
	v_cvt_pk_bf16_f32 v43, v34, v35
	global_store_dwordx4 v[214:215], v[40:43], off offset:256 nt
	v_pk_mul_f32 v[36:37], v[36:37], v[248:249] op_sel_hi:[1,0]
	v_pk_mul_f32 v[38:39], v[38:39], v[248:249] op_sel_hi:[1,0]
	v_pk_mul_f32 v[28:29], v[28:29], v[248:249] op_sel_hi:[1,0]
	v_pk_mul_f32 v[30:31], v[30:31], v[248:249] op_sel_hi:[1,0]
	v_cvt_pk_bf16_f32 v36, v36, v37
	v_cvt_pk_bf16_f32 v37, v38, v39
	v_cvt_pk_bf16_f32 v38, v28, v29
	v_cvt_pk_bf16_f32 v39, v30, v31
	global_store_dwordx4 v[216:217], v[36:39], off nt
	v_pk_mul_f32 v[24:25], v[24:25], v[248:249] op_sel_hi:[1,0]
	v_pk_mul_f32 v[26:27], v[26:27], v[248:249] op_sel_hi:[1,0]
	v_pk_mul_f32 v[16:17], v[16:17], v[248:249] op_sel_hi:[1,0]
	v_pk_mul_f32 v[18:19], v[18:19], v[248:249] op_sel_hi:[1,0]
	v_cvt_pk_bf16_f32 v24, v24, v25
	v_cvt_pk_bf16_f32 v25, v26, v27
	v_cvt_pk_bf16_f32 v26, v16, v17
	v_cvt_pk_bf16_f32 v27, v18, v19
	global_store_dwordx4 v[216:217], v[24:27], off offset:256 nt
	v_pk_mul_f32 v[20:21], v[20:21], v[250:251] op_sel_hi:[1,0]
	v_pk_mul_f32 v[22:23], v[22:23], v[250:251] op_sel_hi:[1,0]
	v_pk_mul_f32 v[12:13], v[12:13], v[250:251] op_sel_hi:[1,0]
	v_pk_mul_f32 v[14:15], v[14:15], v[250:251] op_sel_hi:[1,0]
	v_cvt_pk_bf16_f32 v20, v20, v21
	v_cvt_pk_bf16_f32 v21, v22, v23
	v_cvt_pk_bf16_f32 v22, v12, v13
	v_cvt_pk_bf16_f32 v23, v14, v15
	global_store_dwordx4 v[218:219], v[20:23], off nt
	v_pk_mul_f32 v[8:9], v[8:9], v[250:251] op_sel_hi:[1,0]
	v_pk_mul_f32 v[10:11], v[10:11], v[250:251] op_sel_hi:[1,0]
	v_pk_mul_f32 v[4:5], v[4:5], v[250:251] op_sel_hi:[1,0]
	v_pk_mul_f32 v[6:7], v[6:7], v[250:251] op_sel_hi:[1,0]
	v_cvt_pk_bf16_f32 v8, v8, v9
	v_cvt_pk_bf16_f32 v9, v10, v11
	v_cvt_pk_bf16_f32 v10, v4, v5
	v_cvt_pk_bf16_f32 v11, v6, v7
	global_store_dwordx4 v[218:219], v[8:11], off offset:256 nt
	s_cbranch_vccnz .LBB0_338
	s_andn2_b64 vcc, exec, s[2:3]
	s_cbranch_vccnz .LBB0_337
	s_nop 0
	s_branch .LBB0_337

.Lgu_scales_ready:
	v_lshl_or_b32 v158, s4, 7, v166
	v_ashrrev_i32_e32 v159, 31, v158
	v_lshlrev_b64 v[158:159], 1, v[158:159]
	v_mov_b64_e32 v[154:155], s[20:21]
	s_movk_i32 s6, 0x2c00
	v_mad_i64_i32 v[202:203], s[4:5], v142, s6, v[154:155]
	v_mad_i64_i32 v[204:205], s[4:5], v143, s6, v[154:155]
	v_mad_i64_i32 v[206:207], s[4:5], v144, s6, v[154:155]
	v_mad_i64_i32 v[208:209], s[4:5], v145, s6, v[154:155]
	v_mad_i64_i32 v[210:211], s[4:5], v146, s6, v[154:155]
	v_mad_i64_i32 v[212:213], s[4:5], v147, s6, v[154:155]
	v_mad_i64_i32 v[214:215], s[4:5], v148, s6, v[154:155]
	v_mad_i64_i32 v[216:217], s[4:5], v149, s6, v[154:155]
	v_lshl_add_u64 v[202:203], v[202:203], 0, v[158:159]
	v_lshl_add_u64 v[204:205], v[204:205], 0, v[158:159]
	v_lshl_add_u64 v[206:207], v[206:207], 0, v[158:159]
	v_lshl_add_u64 v[208:209], v[208:209], 0, v[158:159]
	v_lshl_add_u64 v[210:211], v[210:211], 0, v[158:159]
	v_lshl_add_u64 v[212:213], v[212:213], 0, v[158:159]
	v_lshl_add_u64 v[214:215], v[214:215], 0, v[158:159]
	v_lshl_add_u64 v[216:217], v[216:217], 0, v[158:159]
	s_mov_b64 s[42:43], -1
	s_andn2_b64 vcc, exec, s[36:37]
	v_mul_f32_e32 v150, v228, v228
	v_mul_f32_e32 v152, 0xbfb8aa3b, v228
	v_pk_mul_f32 v[218:219], v[124:125], v[152:153] op_sel_hi:[1,0]
	v_pk_mul_f32 v[220:221], v[126:127], v[152:153] op_sel_hi:[1,0]
	v_pk_mul_f32 v[222:223], v[120:121], v[152:153] op_sel_hi:[1,0]
	v_pk_mul_f32 v[224:225], v[122:123], v[152:153] op_sel_hi:[1,0]
	v_exp_f32_e32 v218, v218
	v_exp_f32_e32 v219, v219
	v_exp_f32_e32 v220, v220
	v_exp_f32_e32 v221, v221
	v_exp_f32_e32 v222, v222
	v_exp_f32_e32 v223, v223
	v_exp_f32_e32 v224, v224
	v_exp_f32_e32 v225, v225
	v_pk_add_f32 v[218:219], v[218:219], 1.0 op_sel_hi:[1,0]
	v_pk_add_f32 v[220:221], v[220:221], 1.0 op_sel_hi:[1,0]
	v_pk_add_f32 v[222:223], v[222:223], 1.0 op_sel_hi:[1,0]
	v_pk_add_f32 v[224:225], v[224:225], 1.0 op_sel_hi:[1,0]
	v_rcp_f32_e32 v218, v218
	v_rcp_f32_e32 v219, v219
	v_rcp_f32_e32 v220, v220
	v_rcp_f32_e32 v221, v221
	v_rcp_f32_e32 v222, v222
	v_rcp_f32_e32 v223, v223
	v_rcp_f32_e32 v224, v224
	v_rcp_f32_e32 v225, v225
	v_pk_mul_f32 v[124:125], v[124:125], v[128:129]
	v_pk_mul_f32 v[126:127], v[126:127], v[130:131]
	v_pk_mul_f32 v[120:121], v[120:121], v[116:117]
	v_pk_mul_f32 v[122:123], v[122:123], v[118:119]
	v_pk_mul_f32 v[124:125], v[124:125], v[150:151] op_sel_hi:[1,0]
	v_pk_mul_f32 v[126:127], v[126:127], v[150:151] op_sel_hi:[1,0]
	v_pk_mul_f32 v[120:121], v[120:121], v[150:151] op_sel_hi:[1,0]
	v_pk_mul_f32 v[122:123], v[122:123], v[150:151] op_sel_hi:[1,0]
	v_pk_mul_f32 v[124:125], v[124:125], v[218:219]
	v_pk_mul_f32 v[126:127], v[126:127], v[220:221]
	v_pk_mul_f32 v[120:121], v[120:121], v[222:223]
	v_pk_mul_f32 v[122:123], v[122:123], v[224:225]
	v_cvt_pk_bf16_f32 v124, v124, v125
	v_cvt_pk_bf16_f32 v125, v126, v127
	v_cvt_pk_bf16_f32 v126, v120, v121
	v_cvt_pk_bf16_f32 v127, v122, v123
	s_waitcnt vmcnt(0)
	global_store_dwordx4 v[202:203], v[124:127], off nt
	v_mul_f32_e32 v150, v230, v230
	v_mul_f32_e32 v152, 0xbfb8aa3b, v230
	v_pk_mul_f32 v[218:219], v[112:113], v[152:153] op_sel_hi:[1,0]
	v_pk_mul_f32 v[220:221], v[114:115], v[152:153] op_sel_hi:[1,0]
	v_pk_mul_f32 v[222:223], v[104:105], v[152:153] op_sel_hi:[1,0]
	v_pk_mul_f32 v[224:225], v[106:107], v[152:153] op_sel_hi:[1,0]
	v_exp_f32_e32 v218, v218
	v_exp_f32_e32 v219, v219
	v_exp_f32_e32 v220, v220
	v_exp_f32_e32 v221, v221
	v_exp_f32_e32 v222, v222
	v_exp_f32_e32 v223, v223
	v_exp_f32_e32 v224, v224
	v_exp_f32_e32 v225, v225
	v_pk_add_f32 v[218:219], v[218:219], 1.0 op_sel_hi:[1,0]
	v_pk_add_f32 v[220:221], v[220:221], 1.0 op_sel_hi:[1,0]
	v_pk_add_f32 v[222:223], v[222:223], 1.0 op_sel_hi:[1,0]
	v_pk_add_f32 v[224:225], v[224:225], 1.0 op_sel_hi:[1,0]
	v_rcp_f32_e32 v218, v218
	v_rcp_f32_e32 v219, v219
	v_rcp_f32_e32 v220, v220
	v_rcp_f32_e32 v221, v221
	v_rcp_f32_e32 v222, v222
	v_rcp_f32_e32 v223, v223
	v_rcp_f32_e32 v224, v224
	v_rcp_f32_e32 v225, v225
	v_pk_mul_f32 v[112:113], v[112:113], v[108:109]
	v_pk_mul_f32 v[114:115], v[114:115], v[110:111]
	v_pk_mul_f32 v[104:105], v[104:105], v[100:101]
	v_pk_mul_f32 v[106:107], v[106:107], v[102:103]
	v_pk_mul_f32 v[112:113], v[112:113], v[150:151] op_sel_hi:[1,0]
	v_pk_mul_f32 v[114:115], v[114:115], v[150:151] op_sel_hi:[1,0]
	v_pk_mul_f32 v[104:105], v[104:105], v[150:151] op_sel_hi:[1,0]
	v_pk_mul_f32 v[106:107], v[106:107], v[150:151] op_sel_hi:[1,0]
	v_pk_mul_f32 v[112:113], v[112:113], v[218:219]
	v_pk_mul_f32 v[114:115], v[114:115], v[220:221]
	v_pk_mul_f32 v[104:105], v[104:105], v[222:223]
	v_pk_mul_f32 v[106:107], v[106:107], v[224:225]
	v_cvt_pk_bf16_f32 v112, v112, v113
	v_cvt_pk_bf16_f32 v113, v114, v115
	v_cvt_pk_bf16_f32 v114, v104, v105
	v_cvt_pk_bf16_f32 v115, v106, v107
	global_store_dwordx4 v[204:205], v[112:115], off nt
	v_mul_f32_e32 v150, v238, v238
	v_mul_f32_e32 v152, 0xbfb8aa3b, v238
	v_pk_mul_f32 v[218:219], v[96:97], v[152:153] op_sel_hi:[1,0]
	v_pk_mul_f32 v[220:221], v[98:99], v[152:153] op_sel_hi:[1,0]
	v_pk_mul_f32 v[222:223], v[88:89], v[152:153] op_sel_hi:[1,0]
	v_pk_mul_f32 v[224:225], v[90:91], v[152:153] op_sel_hi:[1,0]
	v_exp_f32_e32 v218, v218
	v_exp_f32_e32 v219, v219
	v_exp_f32_e32 v220, v220
	v_exp_f32_e32 v221, v221
	v_exp_f32_e32 v222, v222
	v_exp_f32_e32 v223, v223
	v_exp_f32_e32 v224, v224
	v_exp_f32_e32 v225, v225
	v_pk_add_f32 v[218:219], v[218:219], 1.0 op_sel_hi:[1,0]
	v_pk_add_f32 v[220:221], v[220:221], 1.0 op_sel_hi:[1,0]
	v_pk_add_f32 v[222:223], v[222:223], 1.0 op_sel_hi:[1,0]
	v_pk_add_f32 v[224:225], v[224:225], 1.0 op_sel_hi:[1,0]
	v_rcp_f32_e32 v218, v218
	v_rcp_f32_e32 v219, v219
	v_rcp_f32_e32 v220, v220
	v_rcp_f32_e32 v221, v221
	v_rcp_f32_e32 v222, v222
	v_rcp_f32_e32 v223, v223
	v_rcp_f32_e32 v224, v224
	v_rcp_f32_e32 v225, v225
	v_pk_mul_f32 v[96:97], v[96:97], v[92:93]
	v_pk_mul_f32 v[98:99], v[98:99], v[94:95]
	v_pk_mul_f32 v[88:89], v[88:89], v[84:85]
	v_pk_mul_f32 v[90:91], v[90:91], v[86:87]
	v_pk_mul_f32 v[96:97], v[96:97], v[150:151] op_sel_hi:[1,0]
	v_pk_mul_f32 v[98:99], v[98:99], v[150:151] op_sel_hi:[1,0]
	v_pk_mul_f32 v[88:89], v[88:89], v[150:151] op_sel_hi:[1,0]
	v_pk_mul_f32 v[90:91], v[90:91], v[150:151] op_sel_hi:[1,0]
	v_pk_mul_f32 v[96:97], v[96:97], v[218:219]
	v_pk_mul_f32 v[98:99], v[98:99], v[220:221]
	v_pk_mul_f32 v[88:89], v[88:89], v[222:223]
	v_pk_mul_f32 v[90:91], v[90:91], v[224:225]
	v_cvt_pk_bf16_f32 v96, v96, v97
	v_cvt_pk_bf16_f32 v97, v98, v99
	v_cvt_pk_bf16_f32 v98, v88, v89
	v_cvt_pk_bf16_f32 v99, v90, v91
	global_store_dwordx4 v[206:207], v[96:99], off nt
	v_mul_f32_e32 v150, v242, v242
	v_mul_f32_e32 v152, 0xbfb8aa3b, v242
	v_pk_mul_f32 v[218:219], v[80:81], v[152:153] op_sel_hi:[1,0]
	v_pk_mul_f32 v[220:221], v[82:83], v[152:153] op_sel_hi:[1,0]
	v_pk_mul_f32 v[222:223], v[72:73], v[152:153] op_sel_hi:[1,0]
	v_pk_mul_f32 v[224:225], v[74:75], v[152:153] op_sel_hi:[1,0]
	v_exp_f32_e32 v218, v218
	v_exp_f32_e32 v219, v219
	v_exp_f32_e32 v220, v220
	v_exp_f32_e32 v221, v221
	v_exp_f32_e32 v222, v222
	v_exp_f32_e32 v223, v223
	v_exp_f32_e32 v224, v224
	v_exp_f32_e32 v225, v225
	v_pk_add_f32 v[218:219], v[218:219], 1.0 op_sel_hi:[1,0]
	v_pk_add_f32 v[220:221], v[220:221], 1.0 op_sel_hi:[1,0]
	v_pk_add_f32 v[222:223], v[222:223], 1.0 op_sel_hi:[1,0]
	v_pk_add_f32 v[224:225], v[224:225], 1.0 op_sel_hi:[1,0]
	v_rcp_f32_e32 v218, v218
	v_rcp_f32_e32 v219, v219
	v_rcp_f32_e32 v220, v220
	v_rcp_f32_e32 v221, v221
	v_rcp_f32_e32 v222, v222
	v_rcp_f32_e32 v223, v223
	v_rcp_f32_e32 v224, v224
	v_rcp_f32_e32 v225, v225
	v_pk_mul_f32 v[80:81], v[80:81], v[76:77]
	v_pk_mul_f32 v[82:83], v[82:83], v[78:79]
	v_pk_mul_f32 v[72:73], v[72:73], v[68:69]
	v_pk_mul_f32 v[74:75], v[74:75], v[70:71]
	v_pk_mul_f32 v[80:81], v[80:81], v[150:151] op_sel_hi:[1,0]
	v_pk_mul_f32 v[82:83], v[82:83], v[150:151] op_sel_hi:[1,0]
	v_pk_mul_f32 v[72:73], v[72:73], v[150:151] op_sel_hi:[1,0]
	v_pk_mul_f32 v[74:75], v[74:75], v[150:151] op_sel_hi:[1,0]
	v_pk_mul_f32 v[80:81], v[80:81], v[218:219]
	v_pk_mul_f32 v[82:83], v[82:83], v[220:221]
	v_pk_mul_f32 v[72:73], v[72:73], v[222:223]
	v_pk_mul_f32 v[74:75], v[74:75], v[224:225]
	v_cvt_pk_bf16_f32 v80, v80, v81
	v_cvt_pk_bf16_f32 v81, v82, v83
	v_cvt_pk_bf16_f32 v82, v72, v73
	v_cvt_pk_bf16_f32 v83, v74, v75
	global_store_dwordx4 v[208:209], v[80:83], off nt
	v_mul_f32_e32 v150, v244, v244
	v_mul_f32_e32 v152, 0xbfb8aa3b, v244
	v_pk_mul_f32 v[218:219], v[64:65], v[152:153] op_sel_hi:[1,0]
	v_pk_mul_f32 v[220:221], v[66:67], v[152:153] op_sel_hi:[1,0]
	v_pk_mul_f32 v[222:223], v[56:57], v[152:153] op_sel_hi:[1,0]
	v_pk_mul_f32 v[224:225], v[58:59], v[152:153] op_sel_hi:[1,0]
	v_exp_f32_e32 v218, v218
	v_exp_f32_e32 v219, v219
	v_exp_f32_e32 v220, v220
	v_exp_f32_e32 v221, v221
	v_exp_f32_e32 v222, v222
	v_exp_f32_e32 v223, v223
	v_exp_f32_e32 v224, v224
	v_exp_f32_e32 v225, v225
	v_pk_add_f32 v[218:219], v[218:219], 1.0 op_sel_hi:[1,0]
	v_pk_add_f32 v[220:221], v[220:221], 1.0 op_sel_hi:[1,0]
	v_pk_add_f32 v[222:223], v[222:223], 1.0 op_sel_hi:[1,0]
	v_pk_add_f32 v[224:225], v[224:225], 1.0 op_sel_hi:[1,0]
	v_rcp_f32_e32 v218, v218
	v_rcp_f32_e32 v219, v219
	v_rcp_f32_e32 v220, v220
	v_rcp_f32_e32 v221, v221
	v_rcp_f32_e32 v222, v222
	v_rcp_f32_e32 v223, v223
	v_rcp_f32_e32 v224, v224
	v_rcp_f32_e32 v225, v225
	v_pk_mul_f32 v[64:65], v[64:65], v[60:61]
	v_pk_mul_f32 v[66:67], v[66:67], v[62:63]
	v_pk_mul_f32 v[56:57], v[56:57], v[52:53]
	v_pk_mul_f32 v[58:59], v[58:59], v[54:55]
	v_pk_mul_f32 v[64:65], v[64:65], v[150:151] op_sel_hi:[1,0]
	v_pk_mul_f32 v[66:67], v[66:67], v[150:151] op_sel_hi:[1,0]
	v_pk_mul_f32 v[56:57], v[56:57], v[150:151] op_sel_hi:[1,0]
	v_pk_mul_f32 v[58:59], v[58:59], v[150:151] op_sel_hi:[1,0]
	v_pk_mul_f32 v[64:65], v[64:65], v[218:219]
	v_pk_mul_f32 v[66:67], v[66:67], v[220:221]
	v_pk_mul_f32 v[56:57], v[56:57], v[222:223]
	v_pk_mul_f32 v[58:59], v[58:59], v[224:225]
	v_cvt_pk_bf16_f32 v64, v64, v65
	v_cvt_pk_bf16_f32 v65, v66, v67
	v_cvt_pk_bf16_f32 v66, v56, v57
	v_cvt_pk_bf16_f32 v67, v58, v59
	global_store_dwordx4 v[210:211], v[64:67], off nt
	v_mul_f32_e32 v150, v246, v246
	v_mul_f32_e32 v152, 0xbfb8aa3b, v246
	v_pk_mul_f32 v[218:219], v[48:49], v[152:153] op_sel_hi:[1,0]
	v_pk_mul_f32 v[220:221], v[50:51], v[152:153] op_sel_hi:[1,0]
	v_pk_mul_f32 v[222:223], v[40:41], v[152:153] op_sel_hi:[1,0]
	v_pk_mul_f32 v[224:225], v[42:43], v[152:153] op_sel_hi:[1,0]
	v_exp_f32_e32 v218, v218
	v_exp_f32_e32 v219, v219
	v_exp_f32_e32 v220, v220
	v_exp_f32_e32 v221, v221
	v_exp_f32_e32 v222, v222
	v_exp_f32_e32 v223, v223
	v_exp_f32_e32 v224, v224
	v_exp_f32_e32 v225, v225
	v_pk_add_f32 v[218:219], v[218:219], 1.0 op_sel_hi:[1,0]
	v_pk_add_f32 v[220:221], v[220:221], 1.0 op_sel_hi:[1,0]
	v_pk_add_f32 v[222:223], v[222:223], 1.0 op_sel_hi:[1,0]
	v_pk_add_f32 v[224:225], v[224:225], 1.0 op_sel_hi:[1,0]
	v_rcp_f32_e32 v218, v218
	v_rcp_f32_e32 v219, v219
	v_rcp_f32_e32 v220, v220
	v_rcp_f32_e32 v221, v221
	v_rcp_f32_e32 v222, v222
	v_rcp_f32_e32 v223, v223
	v_rcp_f32_e32 v224, v224
	v_rcp_f32_e32 v225, v225
	v_pk_mul_f32 v[48:49], v[48:49], v[44:45]
	v_pk_mul_f32 v[50:51], v[50:51], v[46:47]
	v_pk_mul_f32 v[40:41], v[40:41], v[36:37]
	v_pk_mul_f32 v[42:43], v[42:43], v[38:39]
	v_pk_mul_f32 v[48:49], v[48:49], v[150:151] op_sel_hi:[1,0]
	v_pk_mul_f32 v[50:51], v[50:51], v[150:151] op_sel_hi:[1,0]
	v_pk_mul_f32 v[40:41], v[40:41], v[150:151] op_sel_hi:[1,0]
	v_pk_mul_f32 v[42:43], v[42:43], v[150:151] op_sel_hi:[1,0]
	v_pk_mul_f32 v[48:49], v[48:49], v[218:219]
	v_pk_mul_f32 v[50:51], v[50:51], v[220:221]
	v_pk_mul_f32 v[40:41], v[40:41], v[222:223]
	v_pk_mul_f32 v[42:43], v[42:43], v[224:225]
	v_cvt_pk_bf16_f32 v48, v48, v49
	v_cvt_pk_bf16_f32 v49, v50, v51
	v_cvt_pk_bf16_f32 v50, v40, v41
	v_cvt_pk_bf16_f32 v51, v42, v43
	global_store_dwordx4 v[212:213], v[48:51], off nt
	v_mul_f32_e32 v150, v248, v248
	v_mul_f32_e32 v152, 0xbfb8aa3b, v248
	v_pk_mul_f32 v[218:219], v[32:33], v[152:153] op_sel_hi:[1,0]
	v_pk_mul_f32 v[220:221], v[34:35], v[152:153] op_sel_hi:[1,0]
	v_pk_mul_f32 v[222:223], v[24:25], v[152:153] op_sel_hi:[1,0]
	v_pk_mul_f32 v[224:225], v[26:27], v[152:153] op_sel_hi:[1,0]
	v_exp_f32_e32 v218, v218
	v_exp_f32_e32 v219, v219
	v_exp_f32_e32 v220, v220
	v_exp_f32_e32 v221, v221
	v_exp_f32_e32 v222, v222
	v_exp_f32_e32 v223, v223
	v_exp_f32_e32 v224, v224
	v_exp_f32_e32 v225, v225
	v_pk_add_f32 v[218:219], v[218:219], 1.0 op_sel_hi:[1,0]
	v_pk_add_f32 v[220:221], v[220:221], 1.0 op_sel_hi:[1,0]
	v_pk_add_f32 v[222:223], v[222:223], 1.0 op_sel_hi:[1,0]
	v_pk_add_f32 v[224:225], v[224:225], 1.0 op_sel_hi:[1,0]
	v_rcp_f32_e32 v218, v218
	v_rcp_f32_e32 v219, v219
	v_rcp_f32_e32 v220, v220
	v_rcp_f32_e32 v221, v221
	v_rcp_f32_e32 v222, v222
	v_rcp_f32_e32 v223, v223
	v_rcp_f32_e32 v224, v224
	v_rcp_f32_e32 v225, v225
	v_pk_mul_f32 v[32:33], v[32:33], v[28:29]
	v_pk_mul_f32 v[34:35], v[34:35], v[30:31]
	v_pk_mul_f32 v[24:25], v[24:25], v[20:21]
	v_pk_mul_f32 v[26:27], v[26:27], v[22:23]
	v_pk_mul_f32 v[32:33], v[32:33], v[150:151] op_sel_hi:[1,0]
	v_pk_mul_f32 v[34:35], v[34:35], v[150:151] op_sel_hi:[1,0]
	v_pk_mul_f32 v[24:25], v[24:25], v[150:151] op_sel_hi:[1,0]
	v_pk_mul_f32 v[26:27], v[26:27], v[150:151] op_sel_hi:[1,0]
	v_pk_mul_f32 v[32:33], v[32:33], v[218:219]
	v_pk_mul_f32 v[34:35], v[34:35], v[220:221]
	v_pk_mul_f32 v[24:25], v[24:25], v[222:223]
	v_pk_mul_f32 v[26:27], v[26:27], v[224:225]
	v_cvt_pk_bf16_f32 v32, v32, v33
	v_cvt_pk_bf16_f32 v33, v34, v35
	v_cvt_pk_bf16_f32 v34, v24, v25
	v_cvt_pk_bf16_f32 v35, v26, v27
	global_store_dwordx4 v[214:215], v[32:35], off nt
	v_mul_f32_e32 v150, v250, v250
	v_mul_f32_e32 v152, 0xbfb8aa3b, v250
	v_pk_mul_f32 v[218:219], v[16:17], v[152:153] op_sel_hi:[1,0]
	v_pk_mul_f32 v[220:221], v[18:19], v[152:153] op_sel_hi:[1,0]
	v_pk_mul_f32 v[222:223], v[8:9], v[152:153] op_sel_hi:[1,0]
	v_pk_mul_f32 v[224:225], v[10:11], v[152:153] op_sel_hi:[1,0]
	v_exp_f32_e32 v218, v218
	v_exp_f32_e32 v219, v219
	v_exp_f32_e32 v220, v220
	v_exp_f32_e32 v221, v221
	v_exp_f32_e32 v222, v222
	v_exp_f32_e32 v223, v223
	v_exp_f32_e32 v224, v224
	v_exp_f32_e32 v225, v225
	v_pk_add_f32 v[218:219], v[218:219], 1.0 op_sel_hi:[1,0]
	v_pk_add_f32 v[220:221], v[220:221], 1.0 op_sel_hi:[1,0]
	v_pk_add_f32 v[222:223], v[222:223], 1.0 op_sel_hi:[1,0]
	v_pk_add_f32 v[224:225], v[224:225], 1.0 op_sel_hi:[1,0]
	v_rcp_f32_e32 v218, v218
	v_rcp_f32_e32 v219, v219
	v_rcp_f32_e32 v220, v220
	v_rcp_f32_e32 v221, v221
	v_rcp_f32_e32 v222, v222
	v_rcp_f32_e32 v223, v223
	v_rcp_f32_e32 v224, v224
	v_rcp_f32_e32 v225, v225
	v_pk_mul_f32 v[16:17], v[16:17], v[12:13]
	v_pk_mul_f32 v[18:19], v[18:19], v[14:15]
	v_pk_mul_f32 v[8:9], v[8:9], v[4:5]
	v_pk_mul_f32 v[10:11], v[10:11], v[6:7]
	v_pk_mul_f32 v[16:17], v[16:17], v[150:151] op_sel_hi:[1,0]
	v_pk_mul_f32 v[18:19], v[18:19], v[150:151] op_sel_hi:[1,0]
	v_pk_mul_f32 v[8:9], v[8:9], v[150:151] op_sel_hi:[1,0]
	v_pk_mul_f32 v[10:11], v[10:11], v[150:151] op_sel_hi:[1,0]
	v_pk_mul_f32 v[16:17], v[16:17], v[218:219]
	v_pk_mul_f32 v[18:19], v[18:19], v[220:221]
	v_pk_mul_f32 v[8:9], v[8:9], v[222:223]
	v_pk_mul_f32 v[10:11], v[10:11], v[224:225]
	v_cvt_pk_bf16_f32 v16, v16, v17
	v_cvt_pk_bf16_f32 v17, v18, v19
	v_cvt_pk_bf16_f32 v18, v8, v9
	v_cvt_pk_bf16_f32 v19, v10, v11
	global_store_dwordx4 v[216:217], v[16:19], off nt
	s_cbranch_vccnz .LBB0_1062
	s_andn2_b64 vcc, exec, s[2:3]
	s_cbranch_vccnz .LBB0_1061
	s_nop 0
	s_branch .LBB0_1061
